# q/kv -> attention seam: no barrier in front of the two latent queues that do not read q/kv outputs (release + arrive), grid-wide wait in front of the MLA queue; on top of split barriers + group-local
# baseline (speedup 1.0000x reference)
.LBB0_953:
	v_readlane_b32 s4, v255, 15
	s_add_i32 s17, s4, 7
	v_readlane_b32 s4, v255, 0
	v_readlane_b32 s5, v255, 1
	s_cmp_ge_i32 s17, s5
	s_cbranch_scc1 .LBB0_1007
	s_bitcmp0_b32 s32, 0
	s_cbranch_scc1 .Lgb7_slow
	s_waitcnt vmcnt(0) lgkmcnt(0)
	s_barrier
	s_or_b32 s32, s32, 8
	v_cmp_eq_u32_e32 vcc, 0, v0
	s_and_saveexec_b64 s[4:5], vcc
	s_cbranch_execz .Lgb7_join
	s_load_dwordx2 s[8:9], s[0:1], 0xd8
	v_mov_b32_e32 v248, 0
	s_waitcnt lgkmcnt(0)
	s_add_u32 s8, s8, 0x10000
	s_addc_u32 s9, s9, 0
	v_mov_b32_e32 v249, 1
	buffer_wbl2 sc1
	s_waitcnt vmcnt(0)
	global_atomic_add v248, v249, s[8:9] offset:640
.Lgb7_join:
	s_or_b64 exec, exec, s[4:5]
	s_branch .LBB0_1007

.LBB0_1081:
	s_barrier
	s_bitcmp1_b32 s32, 3
	s_cbranch_scc0 .Lgw3_skip
	s_load_dwordx2 s[4:5], s[0:1], 0xd8
	v_mov_b32_e32 v248, 0
	s_waitcnt lgkmcnt(0)
	s_add_u32 s4, s4, 0x10000
	s_addc_u32 s5, s5, 0
	v_readlane_b32 s6, v255, 15
	s_cmp_gt_u32 s6, 6
	s_cselect_b32 s6, 2, 1
	s_lshl_b32 s6, s6, 8
	s_mov_b32 s7, 0
.Lgw3_spin:
	global_load_dword v250, v248, s[4:5] offset:640 sc1
	s_waitcnt vmcnt(0)
	v_readfirstlane_b32 s8, v250
	s_nop 3
	s_cmp_ge_u32 s8, s6
	s_cbranch_scc1 .Lgw3_done
	s_add_i32 s7, s7, 1
	s_cmp_gt_u32 s7, 0x8000
	s_cbranch_scc1 .Lgw3_done
	s_sleep 1
	s_branch .Lgw3_spin
.Lgw3_done:
	buffer_inv sc1
	s_bitset0_b32 s32, 3
.Lgw3_skip:
	s_branch .LBB0_1084
.LBB0_1082:
	s_or_b64 exec, exec, s[6:7]
	s_waitcnt lgkmcnt(0)
	ds_read_b128 v[68:71], v174
	ds_read_b128 v[72:75], v174 offset:32
	v_lshlrev_b32_e32 v85, 9, v169
	v_lshlrev_b32_e32 v86, 1, v161
	v_add3_u32 v85, v171, v85, v86
	s_waitcnt lgkmcnt(1)
	v_rcp_f32_e32 v2, v68
	v_rcp_f32_e32 v76, v69
	v_rcp_f32_e32 v77, v70
	v_rcp_f32_e32 v78, v71
	v_mul_f32_e32 v4, v4, v2
	s_waitcnt lgkmcnt(0)
	v_rcp_f32_e32 v79, v72
	ds_read_b128 v[68:71], v174 offset:64
	v_rcp_f32_e32 v80, v73
	v_rcp_f32_e32 v81, v74
	v_rcp_f32_e32 v82, v75
	ds_read_b128 v[72:75], v174 offset:96
	v_cvt_pk_bf16_f32 v4, v4, v3
	ds_write_b16 v85, v4
	v_mul_f32_e32 v4, v52, v2
	v_cvt_pk_bf16_f32 v4, v4, v3
	ds_write_b16 v85, v4 offset:64
	v_mul_f32_e32 v4, v5, v76
	v_cvt_pk_bf16_f32 v4, v4, v3
	ds_write_b16 v85, v4 offset:128
	v_mul_f32_e32 v4, v53, v76
	v_cvt_pk_bf16_f32 v4, v4, v3
	ds_write_b16 v85, v4 offset:192
	v_mul_f32_e32 v4, v6, v77
	v_cvt_pk_bf16_f32 v4, v4, v3
	ds_write_b16 v85, v4 offset:256
	v_mul_f32_e32 v4, v54, v77
	v_cvt_pk_bf16_f32 v4, v4, v3
	ds_write_b16 v85, v4 offset:320
	v_mul_f32_e32 v4, v7, v78
	v_cvt_pk_bf16_f32 v4, v4, v3
	ds_write_b16 v85, v4 offset:384
	v_mul_f32_e32 v4, v55, v78
	v_cvt_pk_bf16_f32 v4, v4, v3
	ds_write_b16 v85, v4 offset:448
	v_mul_f32_e32 v4, v8, v79
	v_cvt_pk_bf16_f32 v4, v4, v3
	ds_write_b16 v85, v4 offset:1024
	v_mul_f32_e32 v4, v56, v79
	v_cvt_pk_bf16_f32 v4, v4, v3
	ds_write_b16 v85, v4 offset:1088
	v_mul_f32_e32 v4, v9, v80
	v_cvt_pk_bf16_f32 v4, v4, v3
	ds_write_b16 v85, v4 offset:1152
	v_mul_f32_e32 v4, v57, v80
	v_cvt_pk_bf16_f32 v4, v4, v3
	ds_write_b16 v85, v4 offset:1216
	v_mul_f32_e32 v4, v10, v81
	v_cvt_pk_bf16_f32 v4, v4, v3
	ds_write_b16 v85, v4 offset:1280
	v_mul_f32_e32 v4, v58, v81
	v_cvt_pk_bf16_f32 v4, v4, v3
	s_waitcnt lgkmcnt(14)
	v_rcp_f32_e32 v83, v68
	ds_write_b16 v85, v4 offset:1344
	v_mul_f32_e32 v4, v11, v82
	v_cvt_pk_bf16_f32 v4, v4, v3
	ds_write_b16 v85, v4 offset:1408
	v_mul_f32_e32 v4, v59, v82
	v_cvt_pk_bf16_f32 v4, v4, v3
	v_rcp_f32_e32 v84, v69
	ds_write_b16 v85, v4 offset:1472
	v_mul_f32_e32 v4, v12, v83
	v_cvt_pk_bf16_f32 v4, v4, v3
	ds_write_b16 v85, v4 offset:2048
	v_mul_f32_e32 v4, v60, v83
	v_cvt_pk_bf16_f32 v4, v4, v3
	v_rcp_f32_e32 v70, v70
	ds_write_b16 v85, v4 offset:2112
	v_mul_f32_e32 v4, v13, v84
	v_cvt_pk_bf16_f32 v4, v4, v3
	ds_write_b16 v85, v4 offset:2176
	v_mul_f32_e32 v4, v61, v84
	v_cvt_pk_bf16_f32 v4, v4, v3
	v_rcp_f32_e32 v71, v71
	ds_write_b16 v85, v4 offset:2240
	v_mul_f32_e32 v4, v14, v70
	v_cvt_pk_bf16_f32 v4, v4, v3
	ds_write_b16 v85, v4 offset:2304
	v_mul_f32_e32 v4, v62, v70
	v_cvt_pk_bf16_f32 v4, v4, v3
	s_waitcnt lgkmcnt(14)
	v_rcp_f32_e32 v72, v72
	ds_write_b16 v85, v4 offset:2368
	v_mul_f32_e32 v4, v15, v71
	v_cvt_pk_bf16_f32 v4, v4, v3
	ds_write_b16 v85, v4 offset:2432
	v_mul_f32_e32 v4, v63, v71
	v_cvt_pk_bf16_f32 v4, v4, v3
	v_rcp_f32_e32 v73, v73
	ds_write_b16 v85, v4 offset:2496
	v_mul_f32_e32 v4, v16, v72
	v_cvt_pk_bf16_f32 v4, v4, v3
	ds_write_b16 v85, v4 offset:3072
	v_mul_f32_e32 v4, v64, v72
	v_cvt_pk_bf16_f32 v4, v4, v3
	v_rcp_f32_e32 v74, v74
	ds_write_b16 v85, v4 offset:3136
	v_mul_f32_e32 v4, v17, v73
	v_cvt_pk_bf16_f32 v4, v4, v3
	ds_write_b16 v85, v4 offset:3200
	v_mul_f32_e32 v4, v65, v73
	v_cvt_pk_bf16_f32 v4, v4, v3
	v_rcp_f32_e32 v75, v75
	ds_write_b16 v85, v4 offset:3264
	v_mul_f32_e32 v4, v18, v74
	v_cvt_pk_bf16_f32 v4, v4, v3
	ds_write_b16 v85, v4 offset:3328
	v_mul_f32_e32 v4, v66, v74
	v_cvt_pk_bf16_f32 v4, v4, v3
	ds_write_b16 v85, v4 offset:3392
	v_mul_f32_e32 v4, v19, v75
	v_cvt_pk_bf16_f32 v4, v4, v3
	ds_write_b16 v85, v4 offset:3456
	v_mul_f32_e32 v4, v67, v75
	v_add_u32_e32 v87, v171, v160
	v_lshrrev_b32_e32 v89, 3, v168
	v_cvt_pk_bf16_f32 v4, v4, v3
	ds_write_b16 v85, v4 offset:3520
	v_add_u32_e32 v88, s37, v170
	v_lshl_add_u32 v90, v89, 7, v87
	s_waitcnt lgkmcnt(0)
	ds_read_b128 v[4:7], v90
	v_add_u32_e32 v12, v88, v89
	v_mov_b32_e32 v161, v3
	s_lshl_b32 s40, s44, 8
	v_ashrrev_i32_e32 v13, 31, v12
	v_lshl_add_u64 v[68:69], s[8:9], 0, v[160:161]
	s_mov_b64 s[4:5], 0x3d600000
	v_lshl_add_u64 v[8:9], v[12:13], 0, s[40:41]
	v_lshl_add_u64 v[68:69], v[68:69], 0, s[4:5]
	v_lshlrev_b64 v[8:9], 7, v[8:9]
	v_or_b32_e32 v16, 8, v89
	v_lshl_add_u64 v[14:15], v[68:69], 0, v[8:9]
	v_lshl_add_u32 v52, v16, 7, v87
	ds_read_b128 v[8:11], v52
	s_waitcnt lgkmcnt(1)
	global_store_dwordx4 v[14:15], v[4:7], off
	v_add_u32_e32 v14, v88, v16
	v_ashrrev_i32_e32 v15, 31, v14
	v_lshl_add_u64 v[4:5], v[14:15], 0, s[40:41]
	v_lshlrev_b64 v[4:5], 7, v[4:5]
	v_lshl_add_u64 v[4:5], v[68:69], 0, v[4:5]
	s_waitcnt lgkmcnt(0)
	global_store_dwordx4 v[4:5], v[8:11], off
	v_or_b32_e32 v54, 24, v89
	v_lshl_add_u32 v55, v54, 7, v87
	v_or_b32_e32 v8, 16, v89
	v_lshl_add_u32 v53, v8, 7, v87
	ds_read_b128 v[4:7], v53
	v_add_u32_e32 v16, v88, v8
	v_ashrrev_i32_e32 v17, 31, v16
	v_lshl_add_u64 v[8:9], v[16:17], 0, s[40:41]
	v_lshlrev_b64 v[8:9], 7, v[8:9]
	v_lshl_add_u64 v[18:19], v[68:69], 0, v[8:9]
	ds_read_b128 v[8:11], v55
	s_waitcnt lgkmcnt(1)
	global_store_dwordx4 v[18:19], v[4:7], off
	v_add_u32_e32 v18, v88, v54
	v_ashrrev_i32_e32 v19, 31, v18
	v_lshl_add_u64 v[4:5], v[18:19], 0, s[40:41]
	v_lshlrev_b64 v[4:5], 7, v[4:5]
	v_lshl_add_u64 v[4:5], v[68:69], 0, v[4:5]
	s_waitcnt lgkmcnt(0)
	global_store_dwordx4 v[4:5], v[8:11], off
	v_mul_f32_e32 v4, v36, v2
	v_mul_f32_e32 v2, v20, v2
	s_waitcnt lgkmcnt(0)
	v_cvt_pk_bf16_f32 v4, v4, v3
	ds_write_b16 v85, v4
	v_cvt_pk_bf16_f32 v2, v2, v3
	ds_write_b16 v85, v2 offset:64
	v_mul_f32_e32 v2, v37, v76
	v_cvt_pk_bf16_f32 v2, v2, v3
	ds_write_b16 v85, v2 offset:128
	v_mul_f32_e32 v2, v21, v76
	v_cvt_pk_bf16_f32 v2, v2, v3
	ds_write_b16 v85, v2 offset:192
	v_mul_f32_e32 v2, v38, v77
	v_cvt_pk_bf16_f32 v2, v2, v3
	ds_write_b16 v85, v2 offset:256
	v_mul_f32_e32 v2, v22, v77
	v_cvt_pk_bf16_f32 v2, v2, v3
	ds_write_b16 v85, v2 offset:320
	v_mul_f32_e32 v2, v39, v78
	v_cvt_pk_bf16_f32 v2, v2, v3
	ds_write_b16 v85, v2 offset:384
	v_mul_f32_e32 v2, v23, v78
	v_cvt_pk_bf16_f32 v2, v2, v3
	ds_write_b16 v85, v2 offset:448
	v_mul_f32_e32 v2, v40, v79
	v_cvt_pk_bf16_f32 v2, v2, v3
	ds_write_b16 v85, v2 offset:1024
	v_mul_f32_e32 v2, v24, v79
	v_cvt_pk_bf16_f32 v2, v2, v3
	ds_write_b16 v85, v2 offset:1088
	v_mul_f32_e32 v2, v41, v80
	v_cvt_pk_bf16_f32 v2, v2, v3
	ds_write_b16 v85, v2 offset:1152
	v_mul_f32_e32 v2, v25, v80
	v_cvt_pk_bf16_f32 v2, v2, v3
	ds_write_b16 v85, v2 offset:1216
	v_mul_f32_e32 v2, v42, v81
	v_cvt_pk_bf16_f32 v2, v2, v3
	ds_write_b16 v85, v2 offset:1280
	v_mul_f32_e32 v2, v26, v81
	v_cvt_pk_bf16_f32 v2, v2, v3
	ds_write_b16 v85, v2 offset:1344
	v_mul_f32_e32 v2, v43, v82
	v_cvt_pk_bf16_f32 v2, v2, v3
	ds_write_b16 v85, v2 offset:1408
	v_mul_f32_e32 v2, v27, v82
	v_cvt_pk_bf16_f32 v2, v2, v3
	ds_write_b16 v85, v2 offset:1472
	v_mul_f32_e32 v2, v44, v83
	v_cvt_pk_bf16_f32 v2, v2, v3
	ds_write_b16 v85, v2 offset:2048
	v_mul_f32_e32 v2, v28, v83
	v_cvt_pk_bf16_f32 v2, v2, v3
	ds_write_b16 v85, v2 offset:2112
	v_mul_f32_e32 v2, v45, v84
	v_cvt_pk_bf16_f32 v2, v2, v3
	ds_write_b16 v85, v2 offset:2176
	v_mul_f32_e32 v2, v29, v84
	v_cvt_pk_bf16_f32 v2, v2, v3
	ds_write_b16 v85, v2 offset:2240
	v_mul_f32_e32 v2, v46, v70
	v_cvt_pk_bf16_f32 v2, v2, v3
	ds_write_b16 v85, v2 offset:2304
	v_mul_f32_e32 v2, v30, v70
	v_cvt_pk_bf16_f32 v2, v2, v3
	ds_write_b16 v85, v2 offset:2368
	v_mul_f32_e32 v2, v47, v71
	v_cvt_pk_bf16_f32 v2, v2, v3
	ds_write_b16 v85, v2 offset:2432
	v_mul_f32_e32 v2, v31, v71
	v_cvt_pk_bf16_f32 v2, v2, v3
	ds_write_b16 v85, v2 offset:2496
	v_mul_f32_e32 v2, v48, v72
	v_cvt_pk_bf16_f32 v2, v2, v3
	ds_write_b16 v85, v2 offset:3072
	v_mul_f32_e32 v2, v32, v72
	v_cvt_pk_bf16_f32 v2, v2, v3
	ds_write_b16 v85, v2 offset:3136
	v_mul_f32_e32 v2, v49, v73
	v_cvt_pk_bf16_f32 v2, v2, v3
	ds_write_b16 v85, v2 offset:3200
	v_mul_f32_e32 v2, v33, v73
	v_cvt_pk_bf16_f32 v2, v2, v3
	ds_write_b16 v85, v2 offset:3264
	v_mul_f32_e32 v2, v50, v74
	v_cvt_pk_bf16_f32 v2, v2, v3
	ds_write_b16 v85, v2 offset:3328
	v_mul_f32_e32 v2, v34, v74
	v_cvt_pk_bf16_f32 v2, v2, v3
	ds_write_b16 v85, v2 offset:3392
	v_mul_f32_e32 v2, v51, v75
	v_cvt_pk_bf16_f32 v2, v2, v3
	ds_write_b16 v85, v2 offset:3456
	v_mul_f32_e32 v2, v35, v75
	v_cvt_pk_bf16_f32 v2, v2, v3
	ds_write_b16 v85, v2 offset:3520
	s_waitcnt lgkmcnt(0)
	s_bitset1_b32 s40, 14
	ds_read_b128 v[4:7], v90
	v_lshl_add_u64 v[8:9], v[12:13], 0, s[40:41]
	v_lshlrev_b64 v[8:9], 7, v[8:9]
	v_lshl_add_u64 v[12:13], v[68:69], 0, v[8:9]
	ds_read_b128 v[8:11], v52
	s_waitcnt lgkmcnt(1)
	global_store_dwordx4 v[12:13], v[4:7], off
	s_mov_b64 s[4:5], 0
	s_nop 0
	v_lshl_add_u64 v[4:5], v[14:15], 0, s[40:41]
	v_lshlrev_b64 v[4:5], 7, v[4:5]
	v_lshl_add_u64 v[4:5], v[68:69], 0, v[4:5]
	s_waitcnt lgkmcnt(0)
	global_store_dwordx4 v[4:5], v[8:11], off
	ds_read_b128 v[4:7], v53
	s_nop 0
	v_lshl_add_u64 v[8:9], v[16:17], 0, s[40:41]
	v_lshlrev_b64 v[8:9], 7, v[8:9]
	v_lshl_add_u64 v[12:13], v[68:69], 0, v[8:9]
	ds_read_b128 v[8:11], v55
	s_waitcnt lgkmcnt(1)
	global_store_dwordx4 v[12:13], v[4:7], off
	s_nop 1
	v_lshl_add_u64 v[4:5], v[18:19], 0, s[40:41]
	v_lshlrev_b64 v[4:5], 7, v[4:5]
	v_lshl_add_u64 v[4:5], v[68:69], 0, v[4:5]
	s_waitcnt lgkmcnt(0)
	global_store_dwordx4 v[4:5], v[8:11], off
	s_waitcnt lgkmcnt(0)
